# v11 + XCD leaders no longer bump/wait on the per-XCD generation word (unused after the flat poll)
# baseline (speedup 1.0000x reference)
; __device__ __forceinline__ unsigned xb_add(unsigned* p, unsigned v) { return __hip_atomic_fetch_add(p, v, __ATOMIC_RELAXED, __HIP_MEMORY_SCOPE_AGENT); }
; __device__ __forceinline__ void xcd_barrier(const XcdBarrier& b) {
;     ...
;             __builtin_amdgcn_fence(__ATOMIC_ACQUIRE, "agent");
;             xb_add(&bar[XB_XGEN(b.x)], 1u);
.LBB0_175:
	s_or_b64 exec, exec, s[8:9]
	s_mov_b64 s[8:9], exec
	v_mbcnt_lo_u32_b32 v1, s8, 0
	v_mbcnt_hi_u32_b32 v1, s9, v1
	v_cmp_eq_u32_e32 vcc, 0, v1
	s_waitcnt vmcnt(0)
	buffer_inv sc1
	s_and_saveexec_b64 s[12:13], vcc
	s_cbranch_execz .LBB0_177
	s_bcnt1_i32_b64 s0, s[8:9]
	v_mov_b32_e32 v1, 0x2000
	v_mov_b32_e32 v2, s0
.LBB0_177:
	s_or_b64 exec, exec, s[12:13]
	s_waitcnt vmcnt(0)

; __device__ __forceinline__ unsigned xb_add(unsigned* p, unsigned v) { return __hip_atomic_fetch_add(p, v, __ATOMIC_RELAXED, __HIP_MEMORY_SCOPE_AGENT); }
; __device__ __forceinline__ void xcd_barrier(const XcdBarrier& b) {
;     ...
;             __builtin_amdgcn_fence(__ATOMIC_ACQUIRE, "agent");
;             xb_add(&bar[XB_XGEN(b.x)], 1u);
.LBB0_278:
	s_or_b64 exec, exec, s[20:21]
	s_mov_b64 s[20:21], exec
	v_mbcnt_lo_u32_b32 v2, s20, 0
	v_mbcnt_hi_u32_b32 v2, s21, v2
	v_cmp_eq_u32_e32 vcc, 0, v2
	s_waitcnt vmcnt(0)
	buffer_inv sc1
	s_and_saveexec_b64 s[22:23], vcc
	s_cbranch_execz .LBB0_280
	s_bcnt1_i32_b64 s0, s[20:21]
	v_mov_b32_e32 v2, 0x2000
	v_mov_b32_e32 v3, s0
.LBB0_280:
	s_or_b64 exec, exec, s[22:23]
	s_waitcnt vmcnt(0)

; __device__ __forceinline__ unsigned xb_add(unsigned* p, unsigned v) { return __hip_atomic_fetch_add(p, v, __ATOMIC_RELAXED, __HIP_MEMORY_SCOPE_AGENT); }
; __device__ __forceinline__ void xcd_barrier(const XcdBarrier& b) {
;     ...
;             __builtin_amdgcn_fence(__ATOMIC_ACQUIRE, "agent");
;             xb_add(&bar[XB_XGEN(b.x)], 1u);
.LBB0_469:
	s_or_b64 exec, exec, s[8:9]
	s_mov_b64 s[8:9], exec
	v_mbcnt_lo_u32_b32 v2, s8, 0
	v_mbcnt_hi_u32_b32 v2, s9, v2
	v_cmp_eq_u32_e32 vcc, 0, v2
	s_waitcnt vmcnt(0)
	buffer_inv sc1
	s_and_saveexec_b64 s[10:11], vcc
	s_cbranch_execz .LBB0_471
	s_bcnt1_i32_b64 s0, s[8:9]
	v_mov_b32_e32 v2, 0x2000
	v_mov_b32_e32 v3, s0
.LBB0_471:
	s_or_b64 exec, exec, s[10:11]
	s_waitcnt vmcnt(0)

; __device__ __forceinline__ unsigned xb_add(unsigned* p, unsigned v) { return __hip_atomic_fetch_add(p, v, __ATOMIC_RELAXED, __HIP_MEMORY_SCOPE_AGENT); }
; __device__ __forceinline__ void xcd_barrier(const XcdBarrier& b) {
;     ...
;             __builtin_amdgcn_fence(__ATOMIC_ACQUIRE, "agent");
;             xb_add(&bar[XB_XGEN(b.x)], 1u);
.LBB0_564:
	s_or_b64 exec, exec, s[4:5]
	s_mov_b64 s[4:5], exec
	v_mbcnt_lo_u32_b32 v128, s4, 0
	v_mbcnt_hi_u32_b32 v128, s5, v128
	v_cmp_eq_u32_e32 vcc, 0, v128
	s_waitcnt vmcnt(0)
	buffer_inv sc1
	s_and_saveexec_b64 s[12:13], vcc
	s_cbranch_execz .LBB0_566
	s_bcnt1_i32_b64 s4, s[4:5]
	v_mov_b32_e32 v128, 0x2000
	v_mov_b32_e32 v129, s4
.LBB0_566:
	s_or_b64 exec, exec, s[12:13]
	s_waitcnt vmcnt(0)
